# loop-edge edit: second-half P fragment packs issued before the end-of-tile barrier in both attention loops (on top of MLA variant 3 stack)
# baseline (speedup 1.0000x reference)
.LBB0_153:
	v_add_f32_e32 v108, v108, v109
	v_add_f32_e32 v92, v92, v93
	s_waitcnt lgkmcnt(14)
	v_mfma_f32_16x16x32_bf16 v[120:123], v[156:159], v[72:75], v[120:123]
	v_exp_f32_e32 v188, v188
	v_exp_f32_e32 v189, v189
	v_mfma_f32_16x16x32_bf16 v[124:127], v[156:159], v[100:103], v[124:127]
	v_add_f32_e32 v109, v188, v189
	ds_read_b64_tr_b16 v[156:157], v246 offset:28672
	ds_read_b64_tr_b16 v[158:159], v246 offset:29696
	s_waitcnt lgkmcnt(14)
	v_mfma_f32_16x16x32_bf16 v[112:115], v[152:155], v[72:75], v[112:115]
	v_exp_f32_e32 v190, v190
	v_exp_f32_e32 v191, v191
	v_mfma_f32_16x16x32_bf16 v[116:119], v[152:155], v[100:103], v[116:119]
	v_add_f32_e32 v109, v109, v190
	v_add_f32_e32 v109, v109, v191
	ds_read_b64_tr_b16 v[152:153], v245 offset:28672
	ds_read_b64_tr_b16 v[154:155], v245 offset:29696
	s_waitcnt lgkmcnt(14)
	v_mfma_f32_16x16x32_bf16 v[96:99], v[148:151], v[72:75], v[96:99]
	v_exp_f32_e32 v184, v184
	v_exp_f32_e32 v185, v185
	v_mfma_f32_16x16x32_bf16 v[104:107], v[148:151], v[100:103], v[104:107]
	v_add_f32_e32 v109, v109, v184
	v_add_f32_e32 v109, v109, v185
	ds_read_b64_tr_b16 v[148:149], v244 offset:28672
	ds_read_b64_tr_b16 v[150:151], v244 offset:29696
	s_waitcnt lgkmcnt(14)
	v_mfma_f32_16x16x32_bf16 v[84:87], v[144:147], v[72:75], v[84:87]
	v_exp_f32_e32 v186, v186
	v_exp_f32_e32 v187, v187
	v_mfma_f32_16x16x32_bf16 v[88:91], v[144:147], v[100:103], v[88:91]
	v_add_f32_e32 v109, v109, v186
	v_add_f32_e32 v109, v109, v187
	ds_read_b64_tr_b16 v[144:145], v243 offset:28672
	ds_read_b64_tr_b16 v[146:147], v243 offset:29696
	s_waitcnt lgkmcnt(14)
	v_mfma_f32_16x16x32_bf16 v[68:71], v[140:143], v[72:75], v[68:71]
	v_exp_f32_e32 v194, v180
	v_exp_f32_e32 v195, v181
	v_mfma_f32_16x16x32_bf16 v[76:79], v[140:143], v[100:103], v[76:79]
	v_add_f32_e32 v109, v109, v194
	v_add_f32_e32 v109, v109, v195
	ds_read_b64_tr_b16 v[140:141], v242 offset:28672
	ds_read_b64_tr_b16 v[142:143], v242 offset:29696
	s_waitcnt lgkmcnt(14)
	v_mfma_f32_16x16x32_bf16 v[60:63], v[136:139], v[72:75], v[60:63]
	v_exp_f32_e32 v196, v182
	v_exp_f32_e32 v197, v183
	v_mfma_f32_16x16x32_bf16 v[64:67], v[136:139], v[100:103], v[64:67]
	v_add_f32_e32 v109, v109, v196
	v_add_f32_e32 v109, v109, v197
	ds_read_b64_tr_b16 v[136:137], v241 offset:28672
	ds_read_b64_tr_b16 v[138:139], v241 offset:29696
	s_waitcnt lgkmcnt(14)
	v_mfma_f32_16x16x32_bf16 v[48:51], v[132:135], v[72:75], v[48:51]
	v_exp_f32_e32 v172, v172
	v_exp_f32_e32 v173, v173
	v_mfma_f32_16x16x32_bf16 v[52:55], v[132:135], v[100:103], v[52:55]
	v_add_f32_e32 v109, v109, v172
	v_add_f32_e32 v109, v109, v173
	ds_read_b64_tr_b16 v[132:133], v240 offset:28672
	ds_read_b64_tr_b16 v[134:135], v240 offset:29696
	s_waitcnt lgkmcnt(14)
	v_mfma_f32_16x16x32_bf16 v[32:35], v[128:131], v[72:75], v[32:35]
	ds_read_b64_tr_b16 v[180:181], v239 offset:28672
	ds_read_b64_tr_b16 v[182:183], v239 offset:29696
	v_exp_f32_e32 v174, v174
	v_exp_f32_e32 v175, v175
	v_mfma_f32_16x16x32_bf16 v[36:39], v[128:131], v[100:103], v[36:39]
	v_add_f32_e32 v109, v109, v174
	v_add_f32_e32 v109, v109, v175
	s_waitcnt lgkmcnt(14)
	v_mfma_f32_16x16x32_bf16 v[120:123], v[156:159], v[56:59], v[120:123]
	v_exp_f32_e32 v100, v160
	v_exp_f32_e32 v101, v161
	v_cvt_pk_bf16_f32 v72, v188, v189
	v_mfma_f32_16x16x32_bf16 v[124:127], v[156:159], v[80:83], v[124:127]
	v_add_f32_e32 v93, v100, v101
	v_cvt_pk_bf16_f32 v73, v190, v191
	v_cvt_pk_bf16_f32 v74, v184, v185
	v_cvt_pk_bf16_f32 v75, v186, v187
	s_waitcnt lgkmcnt(12)
	v_mfma_f32_16x16x32_bf16 v[112:115], v[152:155], v[56:59], v[112:115]
	v_exp_f32_e32 v102, v162
	v_exp_f32_e32 v103, v163
	v_mfma_f32_16x16x32_bf16 v[116:119], v[152:155], v[80:83], v[116:119]
	v_add_f32_e32 v93, v93, v102
	v_add_f32_e32 v93, v93, v103
	s_waitcnt lgkmcnt(10)
	v_mfma_f32_16x16x32_bf16 v[96:99], v[148:151], v[56:59], v[96:99]
	v_exp_f32_e32 v152, v168
	v_exp_f32_e32 v153, v169
	v_mfma_f32_16x16x32_bf16 v[104:107], v[148:151], v[80:83], v[104:107]
	v_add_f32_e32 v93, v93, v152
	v_add_f32_e32 v93, v93, v153
	s_waitcnt lgkmcnt(8)
	v_mfma_f32_16x16x32_bf16 v[84:87], v[144:147], v[56:59], v[84:87]
	v_exp_f32_e32 v148, v170
	v_exp_f32_e32 v149, v171
	v_mfma_f32_16x16x32_bf16 v[88:91], v[144:147], v[80:83], v[88:91]
	v_add_f32_e32 v93, v93, v148
	v_add_f32_e32 v93, v93, v149
	s_waitcnt lgkmcnt(6)
	v_mfma_f32_16x16x32_bf16 v[68:71], v[140:143], v[56:59], v[68:71]
	v_cvt_pk_bf16_f32 v100, v100, v101
	v_cvt_pk_bf16_f32 v101, v102, v103
	v_cvt_pk_bf16_f32 v102, v152, v153
	v_mfma_f32_16x16x32_bf16 v[76:79], v[140:143], v[80:83], v[76:79]
	v_cvt_pk_bf16_f32 v103, v148, v149
	v_exp_f32_e32 v140, v164
	v_exp_f32_e32 v141, v165
	s_waitcnt lgkmcnt(4)
	v_mfma_f32_16x16x32_bf16 v[60:63], v[136:139], v[56:59], v[60:63]
	v_add_f32_e32 v93, v93, v140
	v_add_f32_e32 v93, v93, v141
	v_exp_f32_e32 v142, v166
	v_exp_f32_e32 v143, v167
	v_mfma_f32_16x16x32_bf16 v[64:67], v[136:139], v[80:83], v[64:67]
	v_add_f32_e32 v93, v93, v142
	v_add_f32_e32 v93, v93, v143
	s_waitcnt lgkmcnt(2)
	v_mfma_f32_16x16x32_bf16 v[48:51], v[132:135], v[56:59], v[48:51]
	v_exp_f32_e32 v136, v176
	v_exp_f32_e32 v137, v177
	v_mfma_f32_16x16x32_bf16 v[52:55], v[132:135], v[80:83], v[52:55]
	v_add_f32_e32 v93, v93, v136
	v_add_f32_e32 v93, v93, v137
	s_waitcnt lgkmcnt(0)
	v_mfma_f32_16x16x32_bf16 v[32:35], v[180:183], v[56:59], v[32:35]
	v_exp_f32_e32 v132, v178
	v_exp_f32_e32 v133, v179
	v_mfma_f32_16x16x32_bf16 v[36:39], v[180:183], v[80:83], v[36:39]
	v_add_f32_e32 v93, v93, v132
	v_add_f32_e32 v93, v93, v133
	v_cvt_pk_bf16_f32 v56, v194, v195
	v_cvt_pk_bf16_f32 v57, v196, v197
	v_cvt_pk_bf16_f32 v58, v172, v173
	v_cvt_pk_bf16_f32 v59, v174, v175
	v_cvt_pk_bf16_f32 v80, v140, v141
	v_cvt_pk_bf16_f32 v81, v142, v143
	v_cvt_pk_bf16_f32 v82, v136, v137
	v_cvt_pk_bf16_f32 v83, v132, v133
	s_waitcnt lgkmcnt(0)
	s_barrier
	s_cmp_lg_u32 s82, s8
	s_cbranch_scc0 .LBB0_139
	s_mov_b32 s1, s8
	s_branch .LBB0_147

.LBB0_196:
	v_mfma_f32_16x16x32_bf16 v[96:99], v[112:115], v[56:59], v[96:99]
	v_exp_f32_e32 v136, v136
	v_exp_f32_e32 v137, v137
	v_exp_f32_e32 v138, v138
	v_mfma_f32_16x16x32_bf16 v[88:91], v[112:115], v[68:71], v[88:91]
	ds_read_b64_tr_b16 v[112:113], v184 offset:24576
	ds_read_b64_tr_b16 v[114:115], v184 offset:25088
	v_exp_f32_e32 v139, v139
	v_mfma_f32_16x16x32_bf16 v[92:95], v[108:111], v[56:59], v[92:95]
	v_exp_f32_e32 v184, v133
	v_exp_f32_e32 v185, v134
	v_exp_f32_e32 v186, v135
	v_mfma_f32_16x16x32_bf16 v[80:83], v[108:111], v[68:71], v[80:83]
	ds_read_b64_tr_b16 v[108:109], v183 offset:24576
	ds_read_b64_tr_b16 v[110:111], v183 offset:25088
	v_exp_f32_e32 v183, v132
	v_mfma_f32_16x16x32_bf16 v[84:87], v[104:107], v[56:59], v[84:87]
	v_exp_f32_e32 v140, v140
	v_exp_f32_e32 v141, v141
	v_exp_f32_e32 v142, v142
	v_mfma_f32_16x16x32_bf16 v[72:75], v[104:107], v[68:71], v[72:75]
	ds_read_b64_tr_b16 v[104:105], v182 offset:24576
	ds_read_b64_tr_b16 v[106:107], v182 offset:25088
	v_exp_f32_e32 v143, v143
	s_mov_b32 s30, s28
	s_mov_b32 s31, s28
	s_mov_b32 s29, s28
	v_mov_b64_e32 v[134:135], s[30:31]
	v_mov_b64_e32 v[132:133], s[28:29]
	v_mfma_f32_16x16x32_bf16 v[40:43], v[100:103], v[56:59], v[40:43]
	v_exp_f32_e32 v144, v144
	v_exp_f32_e32 v145, v145
	v_exp_f32_e32 v146, v146
	v_mfma_f32_16x16x32_bf16 v[44:47], v[100:103], v[68:71], v[44:47]
	ds_read_b64_tr_b16 v[100:101], v181 offset:24576
	ds_read_b64_tr_b16 v[102:103], v181 offset:25088
	v_exp_f32_e32 v147, v147
	v_mfma_f32_16x16x32_bf16 v[76:79], v[132:135], v[56:59], v[76:79]
	v_mfma_f32_16x16x32_bf16 v[60:63], v[132:135], v[68:71], v[60:63]
	v_exp_f32_e32 v68, v120
	v_exp_f32_e32 v69, v121
	s_waitcnt lgkmcnt(6)
	v_mfma_f32_16x16x32_bf16 v[96:99], v[112:115], v[52:55], v[96:99]
	v_exp_f32_e32 v70, v122
	v_exp_f32_e32 v71, v123
	v_cvt_pk_bf16_f32 v56, v136, v137
	v_mfma_f32_16x16x32_bf16 v[88:91], v[112:115], v[64:67], v[88:91]
	v_cvt_pk_bf16_f32 v57, v138, v139
	v_cvt_pk_bf16_f32 v58, v183, v184
	v_cvt_pk_bf16_f32 v59, v185, v186
	s_waitcnt lgkmcnt(4)
	v_mfma_f32_16x16x32_bf16 v[92:95], v[108:111], v[52:55], v[92:95]
	v_exp_f32_e32 v112, v116
	v_exp_f32_e32 v113, v117
	v_exp_f32_e32 v114, v118
	v_mfma_f32_16x16x32_bf16 v[80:83], v[108:111], v[64:67], v[80:83]
	v_exp_f32_e32 v115, v119
	s_waitcnt lgkmcnt(2)
	v_mfma_f32_16x16x32_bf16 v[84:87], v[104:107], v[52:55], v[84:87]
	v_cvt_pk_bf16_f32 v68, v68, v69
	v_cvt_pk_bf16_f32 v69, v70, v71
	v_cvt_pk_bf16_f32 v70, v112, v113
	v_mfma_f32_16x16x32_bf16 v[72:75], v[104:107], v[64:67], v[72:75]
	v_cvt_pk_bf16_f32 v71, v114, v115
	v_exp_f32_e32 v108, v124
	v_exp_f32_e32 v109, v125
	v_exp_f32_e32 v110, v126
	v_exp_f32_e32 v111, v127
	s_waitcnt lgkmcnt(0)
	v_mfma_f32_16x16x32_bf16 v[40:43], v[100:103], v[52:55], v[40:43]
	v_exp_f32_e32 v104, v128
	v_exp_f32_e32 v105, v129
	v_exp_f32_e32 v106, v130
	v_mfma_f32_16x16x32_bf16 v[44:47], v[100:103], v[64:67], v[44:47]
	v_exp_f32_e32 v107, v131
	v_mfma_f32_16x16x32_bf16 v[76:79], v[132:135], v[52:55], v[76:79]
	v_mfma_f32_16x16x32_bf16 v[60:63], v[132:135], v[64:67], v[60:63]
	v_cvt_pk_bf16_f32 v52, v140, v141
	v_cvt_pk_bf16_f32 v53, v142, v143
	v_cvt_pk_bf16_f32 v54, v144, v145
	v_cvt_pk_bf16_f32 v55, v146, v147
	v_cvt_pk_bf16_f32 v64, v108, v109
	v_cvt_pk_bf16_f32 v65, v110, v111
	v_cvt_pk_bf16_f32 v66, v104, v105
	v_cvt_pk_bf16_f32 v67, v106, v107
	s_waitcnt lgkmcnt(0)
	s_barrier
	s_cmp_lg_u32 s82, s10
	s_cbranch_scc0 .LBB0_156
	s_mov_b32 s1, s10
	s_branch .LBB0_190
